# pool mixer sample rows: one row per workgroup over 128 workgroups instead of 8 serial rows on 16
# speedup vs baseline: 1.0189x; 1.0188x over previous
.LBB0_238:
	s_mov_b32 s100, s80
	s_mov_b32 s101, 0
	s_mov_b32 s98, 7
	s_cmp_lt_u32 s25, 0x80
	s_cbranch_scc1 .Lps_go
	s_and_b32 s101, s80, 7
	s_lshr_b32 s80, s80, 3
	s_mov_b32 s98, 0
.Lps_go:
	s_cmp_gt_i32 s80, 15
	s_cbranch_scc1 .Lps_restore
	v_readlane_b32 s2, v252, 30
	s_waitcnt lgkmcnt(0)
	s_add_u32 s16, s16, 0x10000
	v_readlane_b32 s3, v252, 31
	s_mul_i32 s5, s2, 0x78000
	s_addc_u32 s17, s17, 0
	s_mul_hi_i32 s3, s2, 0x78000
	s_add_u32 s27, s16, s5
	v_bfe_u32 v8, v155, 5, 1
	s_addc_u32 s28, s17, s3
	s_lshl_b32 s2, s4, 3
	v_lshl_add_u64 v[78:79], s[6:7], 0, v[96:97]
	s_and_b32 s6, s2, -16
	v_lshlrev_b32_e32 v10, 3, v8
	v_add_u32_e32 v10, s101, v10
	v_or_b32_e32 v82, s6, v10
	s_lshl_b32 s2, s80, 5
	s_lshl_b32 s29, s25, 5
	s_mul_i32 s4, s80, 0x7800
	v_ashrrev_i32_e32 v83, 31, v82
	s_mul_hi_i32 s7, s80, 0x7800
	s_add_u32 s4, s5, s4
	s_addc_u32 s5, s3, s7
	v_lshlrev_b64 v[8:9], 11, v[82:83]
	v_lshl_add_u64 v[8:9], s[4:5], 0, v[8:9]
	v_or_b32_e32 v8, v8, v96
	v_lshl_add_u64 v[86:87], s[16:17], 0, v[8:9]
	v_add3_u32 v8, s6, -8, v10
	v_readlane_b32 s6, v252, 24
	v_lshl_add_u64 v[80:81], s[8:9], 0, v[96:97]
	s_mov_b64 s[8:9], 0x10000
	v_mov_b32_e32 v9, v97
	v_readlane_b32 s7, v252, 25
	v_lshl_add_u64 v[90:91], v[8:9], 0, s[8:9]
	v_mov_b32_e32 v88, v82
	v_lshl_add_u64 v[8:9], s[6:7], 0, v[96:97]
	s_mov_b64 s[6:7], 0x1b200000
	v_mov_b32_e32 v89, v97
	v_add_u32_e32 v92, 8, v82
	v_lshl_add_u64 v[98:99], v[8:9], 0, s[6:7]
	v_lshl_add_u64 v[8:9], s[14:15], 0, v[96:97]
	s_mov_b64 s[6:7], 0x23300000
	v_lshl_add_u64 v[76:77], s[12:13], 0, v[96:97]
	v_or_b32_e32 v130, s98, v82
	v_lshl_add_u64 v[84:85], v[82:83], 0, s[8:9]
	s_mul_hi_i32 s5, s25, 0x7800
	s_mul_i32 s4, s25, 0x7800
	v_ashrrev_i32_e32 v93, 31, v92
	v_lshl_add_u64 v[94:95], v[88:89], 0, s[8:9]
	v_lshl_add_u64 v[100:101], v[8:9], 0, s[6:7]
	s_mov_b32 s30, s80
	s_branch .LBB0_242

.LBB0_242:
	s_lshl_b32 s6, s30, 5
	s_ashr_i32 s3, s2, 31
	s_ashr_i32 s7, s6, 31
	s_add_u32 s6, s6, 0x10000
	s_addc_u32 s7, s7, 0
	s_mul_i32 s8, s30, 0x7800
	v_lshl_add_u64 v[8:9], v[82:83], 0, s[2:3]
	s_mul_hi_i32 s9, s30, 0x7800
	s_add_u32 s8, s27, s8
	v_lshlrev_b64 v[8:9], 11, v[8:9]
	s_addc_u32 s9, s28, s9
	v_lshl_add_u64 v[102:103], v[98:99], 0, v[8:9]
	v_lshl_add_u64 v[104:105], v[100:101], 0, v[8:9]
	s_cmp_lt_i32 s26, 2
	s_mov_b64 s[14:15], -1
	s_cbranch_scc1 .LBB0_340
	v_lshl_add_u64 v[106:107], v[94:95], 0, s[2:3]
	s_cmp_gt_i32 s26, 2
	s_cbranch_scc0 .LBB0_307
	v_lshl_add_u64 v[108:109], v[84:85], 0, s[2:3]
	v_lshl_add_u64 v[110:111], v[90:91], 0, s[2:3]
	v_lshl_add_u64 v[112:113], s[8:9], 0, v[96:97]
	s_mov_b64 s[14:15], 0
	v_mov_b64_e32 v[114:115], v[86:87]
	s_mov_b64 s[16:17], 0
	v_mov_b32_e32 v116, v82
	s_branch .LBB0_246

.Lps_restore:
	s_mov_b32 s80, s100
